# v32 + grid-barrier spin loops poll with s_sleep 3 instead of s_sleep 1 (less traffic on the flag lines)
# speedup vs baseline: 1.0077x; 1.0010x over previous
.LBB0_1466:
	v_readlane_b32 s4, v252, 47
	v_readlane_b32 s5, v252, 48
	s_waitcnt lgkmcnt(0)
	global_load_dword v2, v1, s[22:23] sc1
	global_load_dword v0, v1, s[14:15] sc1
	s_mov_b64 s[6:7], -1
	s_waitcnt vmcnt(0)
	v_add_u32_e32 v17, v0, v2
	global_load_dword v3, v1, s[4:5] sc1
	v_readlane_b32 s4, v252, 49
	v_readlane_b32 s5, v252, 50
	s_waitcnt vmcnt(0)
	v_add_u32_e32 v17, v17, v3
	s_nop 2
	global_load_dword v4, v1, s[4:5] sc1
	v_readlane_b32 s4, v252, 51
	v_readlane_b32 s5, v252, 52
	s_waitcnt vmcnt(0)
	v_add_u32_e32 v17, v17, v4
	s_nop 2
	global_load_dword v5, v1, s[4:5] sc1
	v_readlane_b32 s4, v252, 53
	v_readlane_b32 s5, v252, 54
	s_waitcnt vmcnt(0)
	v_add_u32_e32 v17, v17, v5
	s_nop 2
	global_load_dword v6, v1, s[4:5] sc1
	v_readlane_b32 s4, v252, 55
	v_readlane_b32 s5, v252, 56
	s_waitcnt vmcnt(0)
	v_add_u32_e32 v17, v17, v6
	s_nop 2
	global_load_dword v7, v1, s[4:5] sc1
	v_readlane_b32 s4, v252, 57
	v_readlane_b32 s5, v252, 58
	s_waitcnt vmcnt(0)
	v_add_u32_e32 v17, v17, v7
	s_nop 2
	global_load_dword v8, v1, s[4:5] sc1
	v_readlane_b32 s4, v252, 59
	v_readlane_b32 s5, v252, 60
	s_waitcnt vmcnt(0)
	v_add_u32_e32 v17, v17, v8
	s_nop 2
	global_load_dword v9, v1, s[4:5] sc1
	v_readlane_b32 s4, v252, 61
	v_readlane_b32 s5, v252, 62
	s_waitcnt vmcnt(0)
	v_add_u32_e32 v17, v17, v9
	s_nop 2
	global_load_dword v10, v1, s[4:5] sc1
	v_readlane_b32 s4, v252, 63
	v_readlane_b32 s5, v253, 0
	s_waitcnt vmcnt(0)
	v_add_u32_e32 v17, v17, v10
	s_nop 2
	global_load_dword v11, v1, s[4:5] sc1
	v_readlane_b32 s4, v253, 1
	v_readlane_b32 s5, v253, 2
	s_waitcnt vmcnt(0)
	v_add_u32_e32 v17, v17, v11
	s_nop 2
	global_load_dword v12, v1, s[4:5] sc1
	v_readlane_b32 s4, v253, 3
	v_readlane_b32 s5, v253, 4
	s_waitcnt vmcnt(0)
	v_add_u32_e32 v17, v17, v12
	s_nop 2
	global_load_dword v13, v1, s[4:5] sc1
	v_readlane_b32 s4, v253, 5
	v_readlane_b32 s5, v253, 6
	s_waitcnt vmcnt(0)
	v_add_u32_e32 v17, v17, v13
	s_nop 2
	global_load_dword v14, v1, s[4:5] sc1
	v_readlane_b32 s4, v253, 7
	v_readlane_b32 s5, v253, 8
	s_waitcnt vmcnt(0)
	v_add_u32_e32 v17, v17, v14
	s_nop 2
	global_load_dword v15, v1, s[4:5] sc1
	v_readlane_b32 s4, v253, 9
	v_readlane_b32 s5, v253, 10
	s_waitcnt vmcnt(0)
	v_add_u32_e32 v17, v17, v15
	s_nop 2
	global_load_dword v16, v1, s[4:5] sc1
	s_mov_b64 s[4:5], -1
	s_waitcnt vmcnt(0)
	v_add_u32_e32 v17, v17, v16
	v_cmp_eq_u32_e32 vcc, s19, v17
	s_cbranch_vccnz .LBB0_1465
	s_and_b32 s4, s10, 0xff
	s_cmp_eq_u32 s4, 0
	s_mov_b64 s[4:5], -1
	s_mov_b64 s[8:9], -1
	s_sleep 3
	s_cbranch_scc1 .LBB0_1470
	s_and_b64 vcc, exec, s[8:9]
	s_cbranch_vccz .LBB0_1465

.LBB0_1486:
	s_and_b32 s14, s18, 0xff
	s_mov_b64 s[12:13], -1
	s_cmp_lg_u32 s14, 0
	s_mov_b64 s[16:17], -1
	s_sleep 3
	s_cbranch_scc0 .LBB0_1489
	s_and_b64 vcc, exec, s[16:17]
	s_cbranch_vccz .LBB0_1485

.LBB0_1521:
	v_readlane_b32 s6, v252, 47
	v_readlane_b32 s7, v252, 48
	s_waitcnt lgkmcnt(0)
	global_load_dword v2, v1, s[22:23] sc1
	global_load_dword v0, v1, s[14:15] sc1
	s_mov_b64 s[8:9], -1
	s_waitcnt vmcnt(0)
	v_add_u32_e32 v17, v0, v2
	global_load_dword v3, v1, s[6:7] sc1
	v_readlane_b32 s6, v252, 49
	v_readlane_b32 s7, v252, 50
	s_waitcnt vmcnt(0)
	v_add_u32_e32 v17, v17, v3
	s_nop 2
	global_load_dword v4, v1, s[6:7] sc1
	v_readlane_b32 s6, v252, 51
	v_readlane_b32 s7, v252, 52
	s_waitcnt vmcnt(0)
	v_add_u32_e32 v17, v17, v4
	s_nop 2
	global_load_dword v5, v1, s[6:7] sc1
	v_readlane_b32 s6, v252, 53
	v_readlane_b32 s7, v252, 54
	s_waitcnt vmcnt(0)
	v_add_u32_e32 v17, v17, v5
	s_nop 2
	global_load_dword v6, v1, s[6:7] sc1
	v_readlane_b32 s6, v252, 55
	v_readlane_b32 s7, v252, 56
	s_waitcnt vmcnt(0)
	v_add_u32_e32 v17, v17, v6
	s_nop 2
	global_load_dword v7, v1, s[6:7] sc1
	v_readlane_b32 s6, v252, 57
	v_readlane_b32 s7, v252, 58
	s_waitcnt vmcnt(0)
	v_add_u32_e32 v17, v17, v7
	s_nop 2
	global_load_dword v8, v1, s[6:7] sc1
	v_readlane_b32 s6, v252, 59
	v_readlane_b32 s7, v252, 60
	s_waitcnt vmcnt(0)
	v_add_u32_e32 v17, v17, v8
	s_nop 2
	global_load_dword v9, v1, s[6:7] sc1
	v_readlane_b32 s6, v252, 61
	v_readlane_b32 s7, v252, 62
	s_waitcnt vmcnt(0)
	v_add_u32_e32 v17, v17, v9
	s_nop 2
	global_load_dword v10, v1, s[6:7] sc1
	v_readlane_b32 s6, v252, 63
	v_readlane_b32 s7, v253, 0
	s_waitcnt vmcnt(0)
	v_add_u32_e32 v17, v17, v10
	s_nop 2
	global_load_dword v11, v1, s[6:7] sc1
	v_readlane_b32 s6, v253, 1
	v_readlane_b32 s7, v253, 2
	s_waitcnt vmcnt(0)
	v_add_u32_e32 v17, v17, v11
	s_nop 2
	global_load_dword v12, v1, s[6:7] sc1
	v_readlane_b32 s6, v253, 3
	v_readlane_b32 s7, v253, 4
	s_waitcnt vmcnt(0)
	v_add_u32_e32 v17, v17, v12
	s_nop 2
	global_load_dword v13, v1, s[6:7] sc1
	v_readlane_b32 s6, v253, 5
	v_readlane_b32 s7, v253, 6
	s_waitcnt vmcnt(0)
	v_add_u32_e32 v17, v17, v13
	s_nop 2
	global_load_dword v14, v1, s[6:7] sc1
	v_readlane_b32 s6, v253, 7
	v_readlane_b32 s7, v253, 8
	s_waitcnt vmcnt(0)
	v_add_u32_e32 v17, v17, v14
	s_nop 2
	global_load_dword v15, v1, s[6:7] sc1
	v_readlane_b32 s6, v253, 9
	v_readlane_b32 s7, v253, 10
	s_waitcnt vmcnt(0)
	v_add_u32_e32 v17, v17, v15
	s_nop 2
	global_load_dword v16, v1, s[6:7] sc1
	s_mov_b64 s[6:7], -1
	s_waitcnt vmcnt(0)
	v_add_u32_e32 v17, v17, v16
	v_cmp_eq_u32_e32 vcc, s19, v17
	s_cbranch_vccnz .LBB0_1520
	s_and_b32 s6, s12, 0xff
	s_cmp_eq_u32 s6, 0
	s_mov_b64 s[6:7], -1
	s_mov_b64 s[10:11], -1
	s_sleep 3
	s_cbranch_scc1 .LBB0_1525
	s_and_b64 vcc, exec, s[10:11]
	s_cbranch_vccz .LBB0_1520

.LBB0_1539:
	s_and_b32 s16, s22, 0xff
	s_mov_b64 s[14:15], -1
	s_cmp_lg_u32 s16, 0
	s_mov_b64 s[18:19], -1
	s_sleep 3
	s_cbranch_scc0 .LBB0_1542
	s_and_b64 vcc, exec, s[18:19]
	s_cbranch_vccz .LBB0_1538

.LBB0_1631:
	s_sleep 3
	global_load_dword v2, v1, s[4:5] offset:32 sc1
	s_waitcnt vmcnt(0)
	v_and_b32_e32 v2, 0xffff0000, v2
	v_cmp_ne_u32_e32 vcc, v2, v0
	s_or_b64 s[6:7], vcc, s[6:7]
	s_andn2_b64 exec, exec, s[6:7]
	s_cbranch_execnz .LBB0_1631
